# P0 rmsnorm loop: norm weights hoisted out of the loop, next trip row loads issued before the current reduction (two register sets)
# baseline (speedup 1.0000x reference)
.LBB0_68:
	s_or_b64 exec, exec, s[8:9]
	s_cmpk_gt_i32 s30, 0x7fff
	s_cbranch_scc1 .LBB0_71
	v_mbcnt_lo_u32_b32 v1, -1, 0
	v_mbcnt_hi_u32_b32 v3, -1, v1
	v_and_b32_e32 v1, 64, v3
	v_add_u32_e32 v4, 64, v1
	v_xor_b32_e32 v1, 1, v3
	v_cmp_lt_i32_e32 vcc, v1, v4
	v_xor_b32_e32 v5, 2, v3
	v_readlane_b32 s4, v254, 0
	v_cndmask_b32_e32 v1, v3, v1, vcc
	v_cmp_lt_i32_e32 vcc, v5, v4
	v_readlane_b32 s5, v254, 1
	s_load_dwordx4 s[12:15], s[4:5], 0x0
	s_nop 0
	s_load_dwordx2 s[4:5], s[4:5], 0x48
	v_cndmask_b32_e32 v5, v3, v5, vcc
	v_lshlrev_b32_e32 v11, 2, v5
	v_xor_b32_e32 v5, 4, v3
	v_cmp_lt_i32_e32 vcc, v5, v4
	v_readlane_b32 s8, v254, 10
	v_readlane_b32 s9, v254, 11
	v_cndmask_b32_e32 v5, v3, v5, vcc
	v_lshlrev_b32_e32 v12, 2, v5
	v_xor_b32_e32 v5, 8, v3
	v_cmp_lt_i32_e32 vcc, v5, v4
	v_lshlrev_b32_e32 v6, 4, v23
	v_lshlrev_b32_e32 v1, 2, v1
	v_cndmask_b32_e32 v5, v3, v5, vcc
	v_lshlrev_b32_e32 v13, 2, v5
	v_xor_b32_e32 v5, 16, v3
	v_cmp_lt_i32_e32 vcc, v5, v4
	v_mov_b32_e32 v10, 0x358637bd
	s_nop 0
	v_cndmask_b32_e32 v5, v3, v5, vcc
	v_lshlrev_b32_e32 v14, 2, v5
	v_xor_b32_e32 v5, 32, v3
	v_cmp_lt_i32_e32 vcc, v5, v4
	s_nop 1
	v_cndmask_b32_e32 v3, v3, v5, vcc
	v_lshlrev_b32_e32 v15, 2, v3
	v_mov_b32_e32 v3, 0
	v_mov_b32_e32 v7, v3
	v_lshl_add_u64 v[4:5], s[8:9], 0, v[2:3]
	s_waitcnt lgkmcnt(0)
	v_lshl_add_u64 v[8:9], s[4:5], 0, v[6:7]
	s_ashr_i32 s5, s7, 31
	s_ashr_i32 s8, s31, 31
	s_add_u32 s4, s7, s31
	s_addc_u32 s5, s5, s8
	s_lshl_b64 s[16:17], s[4:5], 12
	s_add_u32 s8, s12, s16
	s_addc_u32 s9, s13, s17
	s_ashr_i32 s7, s6, 31
	s_lshl_b64 s[10:11], s[6:7], 12
	s_lshl_b64 s[4:5], s[4:5], 11
	s_add_u32 s4, s76, s4
	s_addc_u32 s5, s77, s5
	s_lshl_b64 s[12:13], s[6:7], 11
	v_lshl_add_u64 v[2:3], s[4:5], 0, v[2:3]
	s_mov_b64 s[4:5], 0x2400400
	s_add_u32 s14, s14, s16
	v_lshl_add_u64 v[2:3], v[2:3], 0, s[4:5]
	s_addc_u32 s15, s15, s17
	s_mov_b32 s16, 0x3a800000
	s_mov_b32 s7, 0x800000
	global_load_dwordx4 v[132:135], v[8:9], off
	global_load_dwordx4 v[136:139], v[8:9], off offset:1024
	global_load_dwordx4 v[140:143], v[8:9], off offset:2048
	global_load_dwordx4 v[144:147], v[8:9], off offset:3072
	s_add_i32 s4, s30, 0x8000
	s_ashr_i32 s5, s4, 31
	s_lshl_b64 s[4:5], s[4:5], 11
	v_lshl_add_u64 v[148:149], v[4:5], 0, s[4:5]
	v_lshl_add_u64 v[150:151], s[8:9], 0, v[6:7]
	v_lshl_add_u64 v[152:153], s[14:15], 0, v[6:7]
	global_load_dwordx4 v[20:23], v[150:151], off
	global_load_dwordx4 v[24:27], v[152:153], off
	global_load_dwordx4 v[28:31], v[150:151], off offset:1024
	global_load_dwordx4 v[32:35], v[152:153], off offset:1024
	global_load_dwordx4 v[36:39], v[150:151], off offset:3072
	global_load_dwordx4 v[40:43], v[150:151], off offset:2048
	global_load_dwordx4 v[44:47], v[152:153], off offset:3072
	global_load_dwordx4 v[48:51], v[152:153], off offset:2048
	s_add_i32 s30, s30, s6
	s_add_u32 s8, s8, s10
	s_addc_u32 s9, s9, s11
	s_add_u32 s14, s14, s10
	s_addc_u32 s15, s15, s11
	s_waitcnt vmcnt(0)
	s_branch .Lrms_enter_a
.Lrms_loop_a:
	s_waitcnt vmcnt(8)
.Lrms_enter_a:
	s_cmpk_gt_i32 s30, 0x7fff
	s_cbranch_scc1 .Lrms_last_a
	v_lshl_add_u64 v[150:151], s[8:9], 0, v[6:7]
	v_lshl_add_u64 v[152:153], s[14:15], 0, v[6:7]
	global_load_dwordx4 v[100:103], v[150:151], off
	global_load_dwordx4 v[104:107], v[152:153], off
	global_load_dwordx4 v[108:111], v[150:151], off offset:1024
	global_load_dwordx4 v[112:115], v[152:153], off offset:1024
	global_load_dwordx4 v[116:119], v[150:151], off offset:3072
	global_load_dwordx4 v[120:123], v[150:151], off offset:2048
	global_load_dwordx4 v[124:127], v[152:153], off offset:3072
	global_load_dwordx4 v[128:131], v[152:153], off offset:2048
	s_add_i32 s30, s30, s6
	s_add_u32 s8, s8, s10
	s_addc_u32 s9, s9, s11
	s_add_u32 s14, s14, s10
	s_addc_u32 s15, s15, s11
	v_pk_mul_f32 v[54:55], v[22:23], v[22:23]
	v_pk_mul_f32 v[56:57], v[20:21], v[20:21]
	v_pk_mul_f32 v[58:59], v[26:27], v[26:27]
	v_pk_mul_f32 v[60:61], v[24:25], v[24:25]
	v_pk_mul_f32 v[62:63], v[30:31], v[30:31]
	v_pk_mul_f32 v[64:65], v[28:29], v[28:29]
	v_pk_mul_f32 v[66:67], v[34:35], v[34:35]
	v_pk_mul_f32 v[68:69], v[32:33], v[32:33]
	v_pk_mov_b32 v[78:79], v[56:57], v[54:55] op_sel:[1,0]
	v_mov_b32_e32 v57, v55
	v_pk_mov_b32 v[54:55], v[60:61], v[58:59] op_sel:[1,0]
	v_mov_b32_e32 v61, v59
	v_pk_mov_b32 v[58:59], v[64:65], v[62:63] op_sel:[1,0]
	v_mov_b32_e32 v65, v63
	v_pk_mov_b32 v[62:63], v[68:69], v[66:67] op_sel:[1,0]
	v_mov_b32_e32 v69, v67
	v_mul_f32_e32 v77, v36, v36
	v_mul_f32_e32 v70, v41, v41
	v_mul_f32_e32 v72, v43, v43
	v_mul_f32_e32 v74, v49, v49
	v_mul_f32_e32 v76, v51, v51
	v_pk_add_f32 v[56:57], v[78:79], v[56:57]
	v_pk_add_f32 v[54:55], v[54:55], v[60:61]
	v_pk_add_f32 v[58:59], v[58:59], v[64:65]
	v_pk_add_f32 v[60:61], v[62:63], v[68:69]
	v_mul_f32_e32 v80, v37, v37
	v_mul_f32_e32 v81, v38, v38
	v_mul_f32_e32 v82, v39, v39
	v_mul_f32_e32 v83, v44, v44
	v_mul_f32_e32 v84, v45, v45
	v_mul_f32_e32 v85, v46, v46
	v_mul_f32_e32 v86, v47, v47
	v_pk_fma_f32 v[66:67], v[40:41], v[40:41], v[70:71] op_sel_hi:[1,1,0]
	v_pk_fma_f32 v[70:71], v[42:43], v[42:43], v[72:73] op_sel_hi:[1,1,0]
	v_pk_fma_f32 v[72:73], v[48:49], v[48:49], v[74:75] op_sel_hi:[1,1,0]
	v_pk_fma_f32 v[74:75], v[50:51], v[50:51], v[76:77] op_sel_hi:[1,1,0]
	v_pk_add_f32 v[56:57], v[56:57], v[56:57] op_sel:[0,1] op_sel_hi:[1,0]
	v_pk_add_f32 v[58:59], v[58:59], v[58:59] op_sel:[0,1] op_sel_hi:[1,0]
	v_pk_add_f32 v[54:55], v[54:55], v[54:55] op_sel:[0,1] op_sel_hi:[1,0]
	v_pk_add_f32 v[60:61], v[60:61], v[60:61] op_sel:[0,1] op_sel_hi:[1,0]
	v_mov_b32_e32 v67, v81
	v_mov_b32_e32 v71, v82
	v_mov_b32_e32 v73, v85
	v_mov_b32_e32 v75, v86
	v_mov_b32_e32 v57, v77
	v_mov_b32_e32 v59, v80
	v_mov_b32_e32 v55, v83
	v_mov_b32_e32 v61, v84
	v_pk_add_f32 v[62:63], v[66:67], v[70:71]
	v_pk_add_f32 v[64:65], v[72:73], v[74:75]
	v_pk_add_f32 v[56:57], v[56:57], v[58:59]
	v_pk_add_f32 v[54:55], v[54:55], v[60:61]
	v_pk_add_f32 v[56:57], v[56:57], v[62:63]
	v_pk_add_f32 v[54:55], v[54:55], v[64:65]
	v_mov_b32_e32 v59, v56
	v_mov_b32_e32 v58, v54
	v_mov_b32_e32 v56, v55
	v_pk_add_f32 v[54:55], v[58:59], v[56:57]
	ds_bpermute_b32 v57, v1, v55
	ds_bpermute_b32 v56, v1, v54
	s_waitcnt lgkmcnt(0)
	v_pk_add_f32 v[54:55], v[54:55], v[56:57]
	ds_bpermute_b32 v57, v11, v55
	ds_bpermute_b32 v56, v11, v54
	s_waitcnt lgkmcnt(0)
	v_pk_add_f32 v[54:55], v[54:55], v[56:57]
	ds_bpermute_b32 v57, v12, v55
	ds_bpermute_b32 v56, v12, v54
	s_waitcnt lgkmcnt(0)
	v_pk_add_f32 v[54:55], v[54:55], v[56:57]
	ds_bpermute_b32 v57, v13, v55
	ds_bpermute_b32 v56, v13, v54
	s_waitcnt lgkmcnt(0)
	v_pk_add_f32 v[54:55], v[54:55], v[56:57]
	ds_bpermute_b32 v57, v14, v55
	ds_bpermute_b32 v56, v14, v54
	s_waitcnt lgkmcnt(0)
	v_pk_add_f32 v[54:55], v[54:55], v[56:57]
	ds_bpermute_b32 v57, v15, v55
	ds_bpermute_b32 v56, v15, v54
	s_waitcnt lgkmcnt(0)
	v_pk_add_f32 v[54:55], v[54:55], v[56:57]
	s_nop 0
	v_pk_fma_f32 v[54:55], v[54:55], s[16:17], v[10:11] op_sel_hi:[1,0,0]
	s_nop 0
	v_mul_f32_e32 v56, 0x4b800000, v55
	v_cmp_gt_f32_e64 s[4:5], s7, v55
	v_mul_f32_e32 v57, 0x4b800000, v54
	v_cmp_gt_f32_e32 vcc, s7, v54
	v_cndmask_b32_e64 v55, v55, v56, s[4:5]
	v_rsq_f32_e32 v55, v55
	v_cndmask_b32_e32 v54, v54, v57, vcc
	v_rsq_f32_e32 v56, v54
	v_mul_f32_e32 v54, 0x45800000, v55
	v_cndmask_b32_e64 v54, v55, v54, s[4:5]
	v_mul_f32_e32 v57, 0x45800000, v56
	v_cndmask_b32_e32 v56, v56, v57, vcc
	v_pk_mul_f32 v[20:21], v[54:55], v[20:21] op_sel_hi:[0,1]
	v_pk_mul_f32 v[22:23], v[54:55], v[22:23] op_sel_hi:[0,1]
	v_pk_mul_f32 v[24:25], v[56:57], v[24:25] op_sel_hi:[0,1]
	v_pk_mul_f32 v[26:27], v[56:57], v[26:27] op_sel_hi:[0,1]
	v_pk_mul_f32 v[22:23], v[134:135], v[22:23]
	v_pk_mul_f32 v[20:21], v[132:133], v[20:21]
	v_pk_mul_f32 v[26:27], v[134:135], v[26:27]
	v_pk_mul_f32 v[24:25], v[132:133], v[24:25]
	v_cvt_pk_bf16_f32 v20, v20, v21
	v_cvt_pk_bf16_f32 v21, v22, v23
	v_cvt_pk_bf16_f32 v24, v24, v25
	v_cvt_pk_bf16_f32 v25, v26, v27
	global_store_dwordx2 v[2:3], v[20:21], off offset:-1024
	global_store_dwordx2 v[148:149], v[24:25], off
	v_pk_mul_f32 v[28:29], v[54:55], v[28:29] op_sel_hi:[0,1]
	v_pk_mul_f32 v[30:31], v[54:55], v[30:31] op_sel_hi:[0,1]
	v_pk_mul_f32 v[32:33], v[56:57], v[32:33] op_sel_hi:[0,1]
	v_pk_mul_f32 v[34:35], v[56:57], v[34:35] op_sel_hi:[0,1]
	v_pk_mul_f32 v[30:31], v[138:139], v[30:31]
	v_pk_mul_f32 v[28:29], v[136:137], v[28:29]
	v_pk_mul_f32 v[34:35], v[138:139], v[34:35]
	v_pk_mul_f32 v[32:33], v[136:137], v[32:33]
	v_cvt_pk_bf16_f32 v28, v28, v29
	v_cvt_pk_bf16_f32 v29, v30, v31
	v_cvt_pk_bf16_f32 v32, v32, v33
	v_cvt_pk_bf16_f32 v33, v34, v35
	global_store_dwordx2 v[2:3], v[28:29], off offset:-512
	global_store_dwordx2 v[148:149], v[32:33], off offset:512
	v_pk_mul_f32 v[40:41], v[54:55], v[40:41] op_sel_hi:[0,1]
	v_pk_mul_f32 v[42:43], v[54:55], v[42:43] op_sel_hi:[0,1]
	v_pk_mul_f32 v[48:49], v[56:57], v[48:49] op_sel_hi:[0,1]
	v_pk_mul_f32 v[50:51], v[56:57], v[50:51] op_sel_hi:[0,1]
	v_pk_mul_f32 v[42:43], v[142:143], v[42:43]
	v_pk_mul_f32 v[40:41], v[140:141], v[40:41]
	v_pk_mul_f32 v[50:51], v[142:143], v[50:51]
	v_pk_mul_f32 v[48:49], v[140:141], v[48:49]
	v_cvt_pk_bf16_f32 v40, v40, v41
	v_cvt_pk_bf16_f32 v41, v42, v43
	v_cvt_pk_bf16_f32 v48, v48, v49
	v_cvt_pk_bf16_f32 v49, v50, v51
	global_store_dwordx2 v[2:3], v[40:41], off
	global_store_dwordx2 v[148:149], v[48:49], off offset:1024
	v_pk_mul_f32 v[36:37], v[54:55], v[36:37] op_sel_hi:[0,1]
	v_pk_mul_f32 v[38:39], v[54:55], v[38:39] op_sel_hi:[0,1]
	v_pk_mul_f32 v[44:45], v[56:57], v[44:45] op_sel_hi:[0,1]
	v_pk_mul_f32 v[46:47], v[56:57], v[46:47] op_sel_hi:[0,1]
	v_pk_mul_f32 v[38:39], v[146:147], v[38:39]
	v_pk_mul_f32 v[36:37], v[144:145], v[36:37]
	v_pk_mul_f32 v[46:47], v[146:147], v[46:47]
	v_pk_mul_f32 v[44:45], v[144:145], v[44:45]
	v_cvt_pk_bf16_f32 v36, v36, v37
	v_cvt_pk_bf16_f32 v37, v38, v39
	v_cvt_pk_bf16_f32 v44, v44, v45
	v_cvt_pk_bf16_f32 v45, v46, v47
	global_store_dwordx2 v[2:3], v[36:37], off offset:512
	global_store_dwordx2 v[148:149], v[44:45], off offset:1536
	v_lshl_add_u64 v[2:3], v[2:3], 0, s[12:13]
	v_lshl_add_u64 v[148:149], v[148:149], 0, s[12:13]
	s_waitcnt vmcnt(8)
	s_cmpk_gt_i32 s30, 0x7fff
	s_cbranch_scc1 .Lrms_last_b
	v_lshl_add_u64 v[150:151], s[8:9], 0, v[6:7]
	v_lshl_add_u64 v[152:153], s[14:15], 0, v[6:7]
	global_load_dwordx4 v[20:23], v[150:151], off
	global_load_dwordx4 v[24:27], v[152:153], off
	global_load_dwordx4 v[28:31], v[150:151], off offset:1024
	global_load_dwordx4 v[32:35], v[152:153], off offset:1024
	global_load_dwordx4 v[36:39], v[150:151], off offset:3072
	global_load_dwordx4 v[40:43], v[150:151], off offset:2048
	global_load_dwordx4 v[44:47], v[152:153], off offset:3072
	global_load_dwordx4 v[48:51], v[152:153], off offset:2048
	s_add_i32 s30, s30, s6
	s_add_u32 s8, s8, s10
	s_addc_u32 s9, s9, s11
	s_add_u32 s14, s14, s10
	s_addc_u32 s15, s15, s11
	v_pk_mul_f32 v[54:55], v[102:103], v[102:103]
	v_pk_mul_f32 v[56:57], v[100:101], v[100:101]
	v_pk_mul_f32 v[58:59], v[106:107], v[106:107]
	v_pk_mul_f32 v[60:61], v[104:105], v[104:105]
	v_pk_mul_f32 v[62:63], v[110:111], v[110:111]
	v_pk_mul_f32 v[64:65], v[108:109], v[108:109]
	v_pk_mul_f32 v[66:67], v[114:115], v[114:115]
	v_pk_mul_f32 v[68:69], v[112:113], v[112:113]
	v_pk_mov_b32 v[78:79], v[56:57], v[54:55] op_sel:[1,0]
	v_mov_b32_e32 v57, v55
	v_pk_mov_b32 v[54:55], v[60:61], v[58:59] op_sel:[1,0]
	v_mov_b32_e32 v61, v59
	v_pk_mov_b32 v[58:59], v[64:65], v[62:63] op_sel:[1,0]
	v_mov_b32_e32 v65, v63
	v_pk_mov_b32 v[62:63], v[68:69], v[66:67] op_sel:[1,0]
	v_mov_b32_e32 v69, v67
	v_mul_f32_e32 v77, v116, v116
	v_mul_f32_e32 v70, v121, v121
	v_mul_f32_e32 v72, v123, v123
	v_mul_f32_e32 v74, v129, v129
	v_mul_f32_e32 v76, v131, v131
	v_pk_add_f32 v[56:57], v[78:79], v[56:57]
	v_pk_add_f32 v[54:55], v[54:55], v[60:61]
	v_pk_add_f32 v[58:59], v[58:59], v[64:65]
	v_pk_add_f32 v[60:61], v[62:63], v[68:69]
	v_mul_f32_e32 v80, v117, v117
	v_mul_f32_e32 v81, v118, v118
	v_mul_f32_e32 v82, v119, v119
	v_mul_f32_e32 v83, v124, v124
	v_mul_f32_e32 v84, v125, v125
	v_mul_f32_e32 v85, v126, v126
	v_mul_f32_e32 v86, v127, v127
	v_pk_fma_f32 v[66:67], v[120:121], v[120:121], v[70:71] op_sel_hi:[1,1,0]
	v_pk_fma_f32 v[70:71], v[122:123], v[122:123], v[72:73] op_sel_hi:[1,1,0]
	v_pk_fma_f32 v[72:73], v[128:129], v[128:129], v[74:75] op_sel_hi:[1,1,0]
	v_pk_fma_f32 v[74:75], v[130:131], v[130:131], v[76:77] op_sel_hi:[1,1,0]
	v_pk_add_f32 v[56:57], v[56:57], v[56:57] op_sel:[0,1] op_sel_hi:[1,0]
	v_pk_add_f32 v[58:59], v[58:59], v[58:59] op_sel:[0,1] op_sel_hi:[1,0]
	v_pk_add_f32 v[54:55], v[54:55], v[54:55] op_sel:[0,1] op_sel_hi:[1,0]
	v_pk_add_f32 v[60:61], v[60:61], v[60:61] op_sel:[0,1] op_sel_hi:[1,0]
	v_mov_b32_e32 v67, v81
	v_mov_b32_e32 v71, v82
	v_mov_b32_e32 v73, v85
	v_mov_b32_e32 v75, v86
	v_mov_b32_e32 v57, v77
	v_mov_b32_e32 v59, v80
	v_mov_b32_e32 v55, v83
	v_mov_b32_e32 v61, v84
	v_pk_add_f32 v[62:63], v[66:67], v[70:71]
	v_pk_add_f32 v[64:65], v[72:73], v[74:75]
	v_pk_add_f32 v[56:57], v[56:57], v[58:59]
	v_pk_add_f32 v[54:55], v[54:55], v[60:61]
	v_pk_add_f32 v[56:57], v[56:57], v[62:63]
	v_pk_add_f32 v[54:55], v[54:55], v[64:65]
	v_mov_b32_e32 v59, v56
	v_mov_b32_e32 v58, v54
	v_mov_b32_e32 v56, v55
	v_pk_add_f32 v[54:55], v[58:59], v[56:57]
	ds_bpermute_b32 v57, v1, v55
	ds_bpermute_b32 v56, v1, v54
	s_waitcnt lgkmcnt(0)
	v_pk_add_f32 v[54:55], v[54:55], v[56:57]
	ds_bpermute_b32 v57, v11, v55
	ds_bpermute_b32 v56, v11, v54
	s_waitcnt lgkmcnt(0)
	v_pk_add_f32 v[54:55], v[54:55], v[56:57]
	ds_bpermute_b32 v57, v12, v55
	ds_bpermute_b32 v56, v12, v54
	s_waitcnt lgkmcnt(0)
	v_pk_add_f32 v[54:55], v[54:55], v[56:57]
	ds_bpermute_b32 v57, v13, v55
	ds_bpermute_b32 v56, v13, v54
	s_waitcnt lgkmcnt(0)
	v_pk_add_f32 v[54:55], v[54:55], v[56:57]
	ds_bpermute_b32 v57, v14, v55
	ds_bpermute_b32 v56, v14, v54
	s_waitcnt lgkmcnt(0)
	v_pk_add_f32 v[54:55], v[54:55], v[56:57]
	ds_bpermute_b32 v57, v15, v55
	ds_bpermute_b32 v56, v15, v54
	s_waitcnt lgkmcnt(0)
	v_pk_add_f32 v[54:55], v[54:55], v[56:57]
	s_nop 0
	v_pk_fma_f32 v[54:55], v[54:55], s[16:17], v[10:11] op_sel_hi:[1,0,0]
	s_nop 0
	v_mul_f32_e32 v56, 0x4b800000, v55
	v_cmp_gt_f32_e64 s[4:5], s7, v55
	v_mul_f32_e32 v57, 0x4b800000, v54
	v_cmp_gt_f32_e32 vcc, s7, v54
	v_cndmask_b32_e64 v55, v55, v56, s[4:5]
	v_rsq_f32_e32 v55, v55
	v_cndmask_b32_e32 v54, v54, v57, vcc
	v_rsq_f32_e32 v56, v54
	v_mul_f32_e32 v54, 0x45800000, v55
	v_cndmask_b32_e64 v54, v55, v54, s[4:5]
	v_mul_f32_e32 v57, 0x45800000, v56
	v_cndmask_b32_e32 v56, v56, v57, vcc
	v_pk_mul_f32 v[100:101], v[54:55], v[100:101] op_sel_hi:[0,1]
	v_pk_mul_f32 v[102:103], v[54:55], v[102:103] op_sel_hi:[0,1]
	v_pk_mul_f32 v[104:105], v[56:57], v[104:105] op_sel_hi:[0,1]
	v_pk_mul_f32 v[106:107], v[56:57], v[106:107] op_sel_hi:[0,1]
	v_pk_mul_f32 v[102:103], v[134:135], v[102:103]
	v_pk_mul_f32 v[100:101], v[132:133], v[100:101]
	v_pk_mul_f32 v[106:107], v[134:135], v[106:107]
	v_pk_mul_f32 v[104:105], v[132:133], v[104:105]
	v_cvt_pk_bf16_f32 v100, v100, v101
	v_cvt_pk_bf16_f32 v101, v102, v103
	v_cvt_pk_bf16_f32 v104, v104, v105
	v_cvt_pk_bf16_f32 v105, v106, v107
	global_store_dwordx2 v[2:3], v[100:101], off offset:-1024
	global_store_dwordx2 v[148:149], v[104:105], off
	v_pk_mul_f32 v[108:109], v[54:55], v[108:109] op_sel_hi:[0,1]
	v_pk_mul_f32 v[110:111], v[54:55], v[110:111] op_sel_hi:[0,1]
	v_pk_mul_f32 v[112:113], v[56:57], v[112:113] op_sel_hi:[0,1]
	v_pk_mul_f32 v[114:115], v[56:57], v[114:115] op_sel_hi:[0,1]
	v_pk_mul_f32 v[110:111], v[138:139], v[110:111]
	v_pk_mul_f32 v[108:109], v[136:137], v[108:109]
	v_pk_mul_f32 v[114:115], v[138:139], v[114:115]
	v_pk_mul_f32 v[112:113], v[136:137], v[112:113]
	v_cvt_pk_bf16_f32 v108, v108, v109
	v_cvt_pk_bf16_f32 v109, v110, v111
	v_cvt_pk_bf16_f32 v112, v112, v113
	v_cvt_pk_bf16_f32 v113, v114, v115
	global_store_dwordx2 v[2:3], v[108:109], off offset:-512
	global_store_dwordx2 v[148:149], v[112:113], off offset:512
	v_pk_mul_f32 v[120:121], v[54:55], v[120:121] op_sel_hi:[0,1]
	v_pk_mul_f32 v[122:123], v[54:55], v[122:123] op_sel_hi:[0,1]
	v_pk_mul_f32 v[128:129], v[56:57], v[128:129] op_sel_hi:[0,1]
	v_pk_mul_f32 v[130:131], v[56:57], v[130:131] op_sel_hi:[0,1]
	v_pk_mul_f32 v[122:123], v[142:143], v[122:123]
	v_pk_mul_f32 v[120:121], v[140:141], v[120:121]
	v_pk_mul_f32 v[130:131], v[142:143], v[130:131]
	v_pk_mul_f32 v[128:129], v[140:141], v[128:129]
	v_cvt_pk_bf16_f32 v120, v120, v121
	v_cvt_pk_bf16_f32 v121, v122, v123
	v_cvt_pk_bf16_f32 v128, v128, v129
	v_cvt_pk_bf16_f32 v129, v130, v131
	global_store_dwordx2 v[2:3], v[120:121], off
	global_store_dwordx2 v[148:149], v[128:129], off offset:1024
	v_pk_mul_f32 v[116:117], v[54:55], v[116:117] op_sel_hi:[0,1]
	v_pk_mul_f32 v[118:119], v[54:55], v[118:119] op_sel_hi:[0,1]
	v_pk_mul_f32 v[124:125], v[56:57], v[124:125] op_sel_hi:[0,1]
	v_pk_mul_f32 v[126:127], v[56:57], v[126:127] op_sel_hi:[0,1]
	v_pk_mul_f32 v[118:119], v[146:147], v[118:119]
	v_pk_mul_f32 v[116:117], v[144:145], v[116:117]
	v_pk_mul_f32 v[126:127], v[146:147], v[126:127]
	v_pk_mul_f32 v[124:125], v[144:145], v[124:125]
	v_cvt_pk_bf16_f32 v116, v116, v117
	v_cvt_pk_bf16_f32 v117, v118, v119
	v_cvt_pk_bf16_f32 v124, v124, v125
	v_cvt_pk_bf16_f32 v125, v126, v127
	global_store_dwordx2 v[2:3], v[116:117], off offset:512
	global_store_dwordx2 v[148:149], v[124:125], off offset:1536
	v_lshl_add_u64 v[2:3], v[2:3], 0, s[12:13]
	v_lshl_add_u64 v[148:149], v[148:149], 0, s[12:13]
	s_branch .Lrms_loop_a
.Lrms_last_a:
	v_pk_mul_f32 v[54:55], v[22:23], v[22:23]
	v_pk_mul_f32 v[56:57], v[20:21], v[20:21]
	v_pk_mul_f32 v[58:59], v[26:27], v[26:27]
	v_pk_mul_f32 v[60:61], v[24:25], v[24:25]
	v_pk_mul_f32 v[62:63], v[30:31], v[30:31]
	v_pk_mul_f32 v[64:65], v[28:29], v[28:29]
	v_pk_mul_f32 v[66:67], v[34:35], v[34:35]
	v_pk_mul_f32 v[68:69], v[32:33], v[32:33]
	v_pk_mov_b32 v[78:79], v[56:57], v[54:55] op_sel:[1,0]
	v_mov_b32_e32 v57, v55
	v_pk_mov_b32 v[54:55], v[60:61], v[58:59] op_sel:[1,0]
	v_mov_b32_e32 v61, v59
	v_pk_mov_b32 v[58:59], v[64:65], v[62:63] op_sel:[1,0]
	v_mov_b32_e32 v65, v63
	v_pk_mov_b32 v[62:63], v[68:69], v[66:67] op_sel:[1,0]
	v_mov_b32_e32 v69, v67
	v_mul_f32_e32 v77, v36, v36
	v_mul_f32_e32 v70, v41, v41
	v_mul_f32_e32 v72, v43, v43
	v_mul_f32_e32 v74, v49, v49
	v_mul_f32_e32 v76, v51, v51
	v_pk_add_f32 v[56:57], v[78:79], v[56:57]
	v_pk_add_f32 v[54:55], v[54:55], v[60:61]
	v_pk_add_f32 v[58:59], v[58:59], v[64:65]
	v_pk_add_f32 v[60:61], v[62:63], v[68:69]
	v_mul_f32_e32 v80, v37, v37
	v_mul_f32_e32 v81, v38, v38
	v_mul_f32_e32 v82, v39, v39
	v_mul_f32_e32 v83, v44, v44
	v_mul_f32_e32 v84, v45, v45
	v_mul_f32_e32 v85, v46, v46
	v_mul_f32_e32 v86, v47, v47
	v_pk_fma_f32 v[66:67], v[40:41], v[40:41], v[70:71] op_sel_hi:[1,1,0]
	v_pk_fma_f32 v[70:71], v[42:43], v[42:43], v[72:73] op_sel_hi:[1,1,0]
	v_pk_fma_f32 v[72:73], v[48:49], v[48:49], v[74:75] op_sel_hi:[1,1,0]
	v_pk_fma_f32 v[74:75], v[50:51], v[50:51], v[76:77] op_sel_hi:[1,1,0]
	v_pk_add_f32 v[56:57], v[56:57], v[56:57] op_sel:[0,1] op_sel_hi:[1,0]
	v_pk_add_f32 v[58:59], v[58:59], v[58:59] op_sel:[0,1] op_sel_hi:[1,0]
	v_pk_add_f32 v[54:55], v[54:55], v[54:55] op_sel:[0,1] op_sel_hi:[1,0]
	v_pk_add_f32 v[60:61], v[60:61], v[60:61] op_sel:[0,1] op_sel_hi:[1,0]
	v_mov_b32_e32 v67, v81
	v_mov_b32_e32 v71, v82
	v_mov_b32_e32 v73, v85
	v_mov_b32_e32 v75, v86
	v_mov_b32_e32 v57, v77
	v_mov_b32_e32 v59, v80
	v_mov_b32_e32 v55, v83
	v_mov_b32_e32 v61, v84
	v_pk_add_f32 v[62:63], v[66:67], v[70:71]
	v_pk_add_f32 v[64:65], v[72:73], v[74:75]
	v_pk_add_f32 v[56:57], v[56:57], v[58:59]
	v_pk_add_f32 v[54:55], v[54:55], v[60:61]
	v_pk_add_f32 v[56:57], v[56:57], v[62:63]
	v_pk_add_f32 v[54:55], v[54:55], v[64:65]
	v_mov_b32_e32 v59, v56
	v_mov_b32_e32 v58, v54
	v_mov_b32_e32 v56, v55
	v_pk_add_f32 v[54:55], v[58:59], v[56:57]
	ds_bpermute_b32 v57, v1, v55
	ds_bpermute_b32 v56, v1, v54
	s_waitcnt lgkmcnt(0)
	v_pk_add_f32 v[54:55], v[54:55], v[56:57]
	ds_bpermute_b32 v57, v11, v55
	ds_bpermute_b32 v56, v11, v54
	s_waitcnt lgkmcnt(0)
	v_pk_add_f32 v[54:55], v[54:55], v[56:57]
	ds_bpermute_b32 v57, v12, v55
	ds_bpermute_b32 v56, v12, v54
	s_waitcnt lgkmcnt(0)
	v_pk_add_f32 v[54:55], v[54:55], v[56:57]
	ds_bpermute_b32 v57, v13, v55
	ds_bpermute_b32 v56, v13, v54
	s_waitcnt lgkmcnt(0)
	v_pk_add_f32 v[54:55], v[54:55], v[56:57]
	ds_bpermute_b32 v57, v14, v55
	ds_bpermute_b32 v56, v14, v54
	s_waitcnt lgkmcnt(0)
	v_pk_add_f32 v[54:55], v[54:55], v[56:57]
	ds_bpermute_b32 v57, v15, v55
	ds_bpermute_b32 v56, v15, v54
	s_waitcnt lgkmcnt(0)
	v_pk_add_f32 v[54:55], v[54:55], v[56:57]
	s_nop 0
	v_pk_fma_f32 v[54:55], v[54:55], s[16:17], v[10:11] op_sel_hi:[1,0,0]
	s_nop 0
	v_mul_f32_e32 v56, 0x4b800000, v55
	v_cmp_gt_f32_e64 s[4:5], s7, v55
	v_mul_f32_e32 v57, 0x4b800000, v54
	v_cmp_gt_f32_e32 vcc, s7, v54
	v_cndmask_b32_e64 v55, v55, v56, s[4:5]
	v_rsq_f32_e32 v55, v55
	v_cndmask_b32_e32 v54, v54, v57, vcc
	v_rsq_f32_e32 v56, v54
	v_mul_f32_e32 v54, 0x45800000, v55
	v_cndmask_b32_e64 v54, v55, v54, s[4:5]
	v_mul_f32_e32 v57, 0x45800000, v56
	v_cndmask_b32_e32 v56, v56, v57, vcc
	v_pk_mul_f32 v[20:21], v[54:55], v[20:21] op_sel_hi:[0,1]
	v_pk_mul_f32 v[22:23], v[54:55], v[22:23] op_sel_hi:[0,1]
	v_pk_mul_f32 v[24:25], v[56:57], v[24:25] op_sel_hi:[0,1]
	v_pk_mul_f32 v[26:27], v[56:57], v[26:27] op_sel_hi:[0,1]
	v_pk_mul_f32 v[22:23], v[134:135], v[22:23]
	v_pk_mul_f32 v[20:21], v[132:133], v[20:21]
	v_pk_mul_f32 v[26:27], v[134:135], v[26:27]
	v_pk_mul_f32 v[24:25], v[132:133], v[24:25]
	v_cvt_pk_bf16_f32 v20, v20, v21
	v_cvt_pk_bf16_f32 v21, v22, v23
	v_cvt_pk_bf16_f32 v24, v24, v25
	v_cvt_pk_bf16_f32 v25, v26, v27
	global_store_dwordx2 v[2:3], v[20:21], off offset:-1024
	global_store_dwordx2 v[148:149], v[24:25], off
	v_pk_mul_f32 v[28:29], v[54:55], v[28:29] op_sel_hi:[0,1]
	v_pk_mul_f32 v[30:31], v[54:55], v[30:31] op_sel_hi:[0,1]
	v_pk_mul_f32 v[32:33], v[56:57], v[32:33] op_sel_hi:[0,1]
	v_pk_mul_f32 v[34:35], v[56:57], v[34:35] op_sel_hi:[0,1]
	v_pk_mul_f32 v[30:31], v[138:139], v[30:31]
	v_pk_mul_f32 v[28:29], v[136:137], v[28:29]
	v_pk_mul_f32 v[34:35], v[138:139], v[34:35]
	v_pk_mul_f32 v[32:33], v[136:137], v[32:33]
	v_cvt_pk_bf16_f32 v28, v28, v29
	v_cvt_pk_bf16_f32 v29, v30, v31
	v_cvt_pk_bf16_f32 v32, v32, v33
	v_cvt_pk_bf16_f32 v33, v34, v35
	global_store_dwordx2 v[2:3], v[28:29], off offset:-512
	global_store_dwordx2 v[148:149], v[32:33], off offset:512
	v_pk_mul_f32 v[40:41], v[54:55], v[40:41] op_sel_hi:[0,1]
	v_pk_mul_f32 v[42:43], v[54:55], v[42:43] op_sel_hi:[0,1]
	v_pk_mul_f32 v[48:49], v[56:57], v[48:49] op_sel_hi:[0,1]
	v_pk_mul_f32 v[50:51], v[56:57], v[50:51] op_sel_hi:[0,1]
	v_pk_mul_f32 v[42:43], v[142:143], v[42:43]
	v_pk_mul_f32 v[40:41], v[140:141], v[40:41]
	v_pk_mul_f32 v[50:51], v[142:143], v[50:51]
	v_pk_mul_f32 v[48:49], v[140:141], v[48:49]
	v_cvt_pk_bf16_f32 v40, v40, v41
	v_cvt_pk_bf16_f32 v41, v42, v43
	v_cvt_pk_bf16_f32 v48, v48, v49
	v_cvt_pk_bf16_f32 v49, v50, v51
	global_store_dwordx2 v[2:3], v[40:41], off
	global_store_dwordx2 v[148:149], v[48:49], off offset:1024
	v_pk_mul_f32 v[36:37], v[54:55], v[36:37] op_sel_hi:[0,1]
	v_pk_mul_f32 v[38:39], v[54:55], v[38:39] op_sel_hi:[0,1]
	v_pk_mul_f32 v[44:45], v[56:57], v[44:45] op_sel_hi:[0,1]
	v_pk_mul_f32 v[46:47], v[56:57], v[46:47] op_sel_hi:[0,1]
	v_pk_mul_f32 v[38:39], v[146:147], v[38:39]
	v_pk_mul_f32 v[36:37], v[144:145], v[36:37]
	v_pk_mul_f32 v[46:47], v[146:147], v[46:47]
	v_pk_mul_f32 v[44:45], v[144:145], v[44:45]
	v_cvt_pk_bf16_f32 v36, v36, v37
	v_cvt_pk_bf16_f32 v37, v38, v39
	v_cvt_pk_bf16_f32 v44, v44, v45
	v_cvt_pk_bf16_f32 v45, v46, v47
	global_store_dwordx2 v[2:3], v[36:37], off offset:512
	global_store_dwordx2 v[148:149], v[44:45], off offset:1536
	v_lshl_add_u64 v[2:3], v[2:3], 0, s[12:13]
	v_lshl_add_u64 v[148:149], v[148:149], 0, s[12:13]
	s_branch .Lrms_done
.Lrms_last_b:
	v_pk_mul_f32 v[54:55], v[102:103], v[102:103]
	v_pk_mul_f32 v[56:57], v[100:101], v[100:101]
	v_pk_mul_f32 v[58:59], v[106:107], v[106:107]
	v_pk_mul_f32 v[60:61], v[104:105], v[104:105]
	v_pk_mul_f32 v[62:63], v[110:111], v[110:111]
	v_pk_mul_f32 v[64:65], v[108:109], v[108:109]
	v_pk_mul_f32 v[66:67], v[114:115], v[114:115]
	v_pk_mul_f32 v[68:69], v[112:113], v[112:113]
	v_pk_mov_b32 v[78:79], v[56:57], v[54:55] op_sel:[1,0]
	v_mov_b32_e32 v57, v55
	v_pk_mov_b32 v[54:55], v[60:61], v[58:59] op_sel:[1,0]
	v_mov_b32_e32 v61, v59
	v_pk_mov_b32 v[58:59], v[64:65], v[62:63] op_sel:[1,0]
	v_mov_b32_e32 v65, v63
	v_pk_mov_b32 v[62:63], v[68:69], v[66:67] op_sel:[1,0]
	v_mov_b32_e32 v69, v67
	v_mul_f32_e32 v77, v116, v116
	v_mul_f32_e32 v70, v121, v121
	v_mul_f32_e32 v72, v123, v123
	v_mul_f32_e32 v74, v129, v129
	v_mul_f32_e32 v76, v131, v131
	v_pk_add_f32 v[56:57], v[78:79], v[56:57]
	v_pk_add_f32 v[54:55], v[54:55], v[60:61]
	v_pk_add_f32 v[58:59], v[58:59], v[64:65]
	v_pk_add_f32 v[60:61], v[62:63], v[68:69]
	v_mul_f32_e32 v80, v117, v117
	v_mul_f32_e32 v81, v118, v118
	v_mul_f32_e32 v82, v119, v119
	v_mul_f32_e32 v83, v124, v124
	v_mul_f32_e32 v84, v125, v125
	v_mul_f32_e32 v85, v126, v126
	v_mul_f32_e32 v86, v127, v127
	v_pk_fma_f32 v[66:67], v[120:121], v[120:121], v[70:71] op_sel_hi:[1,1,0]
	v_pk_fma_f32 v[70:71], v[122:123], v[122:123], v[72:73] op_sel_hi:[1,1,0]
	v_pk_fma_f32 v[72:73], v[128:129], v[128:129], v[74:75] op_sel_hi:[1,1,0]
	v_pk_fma_f32 v[74:75], v[130:131], v[130:131], v[76:77] op_sel_hi:[1,1,0]
	v_pk_add_f32 v[56:57], v[56:57], v[56:57] op_sel:[0,1] op_sel_hi:[1,0]
	v_pk_add_f32 v[58:59], v[58:59], v[58:59] op_sel:[0,1] op_sel_hi:[1,0]
	v_pk_add_f32 v[54:55], v[54:55], v[54:55] op_sel:[0,1] op_sel_hi:[1,0]
	v_pk_add_f32 v[60:61], v[60:61], v[60:61] op_sel:[0,1] op_sel_hi:[1,0]
	v_mov_b32_e32 v67, v81
	v_mov_b32_e32 v71, v82
	v_mov_b32_e32 v73, v85
	v_mov_b32_e32 v75, v86
	v_mov_b32_e32 v57, v77
	v_mov_b32_e32 v59, v80
	v_mov_b32_e32 v55, v83
	v_mov_b32_e32 v61, v84
	v_pk_add_f32 v[62:63], v[66:67], v[70:71]
	v_pk_add_f32 v[64:65], v[72:73], v[74:75]
	v_pk_add_f32 v[56:57], v[56:57], v[58:59]
	v_pk_add_f32 v[54:55], v[54:55], v[60:61]
	v_pk_add_f32 v[56:57], v[56:57], v[62:63]
	v_pk_add_f32 v[54:55], v[54:55], v[64:65]
	v_mov_b32_e32 v59, v56
	v_mov_b32_e32 v58, v54
	v_mov_b32_e32 v56, v55
	v_pk_add_f32 v[54:55], v[58:59], v[56:57]
	ds_bpermute_b32 v57, v1, v55
	ds_bpermute_b32 v56, v1, v54
	s_waitcnt lgkmcnt(0)
	v_pk_add_f32 v[54:55], v[54:55], v[56:57]
	ds_bpermute_b32 v57, v11, v55
	ds_bpermute_b32 v56, v11, v54
	s_waitcnt lgkmcnt(0)
	v_pk_add_f32 v[54:55], v[54:55], v[56:57]
	ds_bpermute_b32 v57, v12, v55
	ds_bpermute_b32 v56, v12, v54
	s_waitcnt lgkmcnt(0)
	v_pk_add_f32 v[54:55], v[54:55], v[56:57]
	ds_bpermute_b32 v57, v13, v55
	ds_bpermute_b32 v56, v13, v54
	s_waitcnt lgkmcnt(0)
	v_pk_add_f32 v[54:55], v[54:55], v[56:57]
	ds_bpermute_b32 v57, v14, v55
	ds_bpermute_b32 v56, v14, v54
	s_waitcnt lgkmcnt(0)
	v_pk_add_f32 v[54:55], v[54:55], v[56:57]
	ds_bpermute_b32 v57, v15, v55
	ds_bpermute_b32 v56, v15, v54
	s_waitcnt lgkmcnt(0)
	v_pk_add_f32 v[54:55], v[54:55], v[56:57]
	s_nop 0
	v_pk_fma_f32 v[54:55], v[54:55], s[16:17], v[10:11] op_sel_hi:[1,0,0]
	s_nop 0
	v_mul_f32_e32 v56, 0x4b800000, v55
	v_cmp_gt_f32_e64 s[4:5], s7, v55
	v_mul_f32_e32 v57, 0x4b800000, v54
	v_cmp_gt_f32_e32 vcc, s7, v54
	v_cndmask_b32_e64 v55, v55, v56, s[4:5]
	v_rsq_f32_e32 v55, v55
	v_cndmask_b32_e32 v54, v54, v57, vcc
	v_rsq_f32_e32 v56, v54
	v_mul_f32_e32 v54, 0x45800000, v55
	v_cndmask_b32_e64 v54, v55, v54, s[4:5]
	v_mul_f32_e32 v57, 0x45800000, v56
	v_cndmask_b32_e32 v56, v56, v57, vcc
	v_pk_mul_f32 v[100:101], v[54:55], v[100:101] op_sel_hi:[0,1]
	v_pk_mul_f32 v[102:103], v[54:55], v[102:103] op_sel_hi:[0,1]
	v_pk_mul_f32 v[104:105], v[56:57], v[104:105] op_sel_hi:[0,1]
	v_pk_mul_f32 v[106:107], v[56:57], v[106:107] op_sel_hi:[0,1]
	v_pk_mul_f32 v[102:103], v[134:135], v[102:103]
	v_pk_mul_f32 v[100:101], v[132:133], v[100:101]
	v_pk_mul_f32 v[106:107], v[134:135], v[106:107]
	v_pk_mul_f32 v[104:105], v[132:133], v[104:105]
	v_cvt_pk_bf16_f32 v100, v100, v101
	v_cvt_pk_bf16_f32 v101, v102, v103
	v_cvt_pk_bf16_f32 v104, v104, v105
	v_cvt_pk_bf16_f32 v105, v106, v107
	global_store_dwordx2 v[2:3], v[100:101], off offset:-1024
	global_store_dwordx2 v[148:149], v[104:105], off
	v_pk_mul_f32 v[108:109], v[54:55], v[108:109] op_sel_hi:[0,1]
	v_pk_mul_f32 v[110:111], v[54:55], v[110:111] op_sel_hi:[0,1]
	v_pk_mul_f32 v[112:113], v[56:57], v[112:113] op_sel_hi:[0,1]
	v_pk_mul_f32 v[114:115], v[56:57], v[114:115] op_sel_hi:[0,1]
	v_pk_mul_f32 v[110:111], v[138:139], v[110:111]
	v_pk_mul_f32 v[108:109], v[136:137], v[108:109]
	v_pk_mul_f32 v[114:115], v[138:139], v[114:115]
	v_pk_mul_f32 v[112:113], v[136:137], v[112:113]
	v_cvt_pk_bf16_f32 v108, v108, v109
	v_cvt_pk_bf16_f32 v109, v110, v111
	v_cvt_pk_bf16_f32 v112, v112, v113
	v_cvt_pk_bf16_f32 v113, v114, v115
	global_store_dwordx2 v[2:3], v[108:109], off offset:-512
	global_store_dwordx2 v[148:149], v[112:113], off offset:512
	v_pk_mul_f32 v[120:121], v[54:55], v[120:121] op_sel_hi:[0,1]
	v_pk_mul_f32 v[122:123], v[54:55], v[122:123] op_sel_hi:[0,1]
	v_pk_mul_f32 v[128:129], v[56:57], v[128:129] op_sel_hi:[0,1]
	v_pk_mul_f32 v[130:131], v[56:57], v[130:131] op_sel_hi:[0,1]
	v_pk_mul_f32 v[122:123], v[142:143], v[122:123]
	v_pk_mul_f32 v[120:121], v[140:141], v[120:121]
	v_pk_mul_f32 v[130:131], v[142:143], v[130:131]
	v_pk_mul_f32 v[128:129], v[140:141], v[128:129]
	v_cvt_pk_bf16_f32 v120, v120, v121
	v_cvt_pk_bf16_f32 v121, v122, v123
	v_cvt_pk_bf16_f32 v128, v128, v129
	v_cvt_pk_bf16_f32 v129, v130, v131
	global_store_dwordx2 v[2:3], v[120:121], off
	global_store_dwordx2 v[148:149], v[128:129], off offset:1024
	v_pk_mul_f32 v[116:117], v[54:55], v[116:117] op_sel_hi:[0,1]
	v_pk_mul_f32 v[118:119], v[54:55], v[118:119] op_sel_hi:[0,1]
	v_pk_mul_f32 v[124:125], v[56:57], v[124:125] op_sel_hi:[0,1]
	v_pk_mul_f32 v[126:127], v[56:57], v[126:127] op_sel_hi:[0,1]
	v_pk_mul_f32 v[118:119], v[146:147], v[118:119]
	v_pk_mul_f32 v[116:117], v[144:145], v[116:117]
	v_pk_mul_f32 v[126:127], v[146:147], v[126:127]
	v_pk_mul_f32 v[124:125], v[144:145], v[124:125]
	v_cvt_pk_bf16_f32 v116, v116, v117
	v_cvt_pk_bf16_f32 v117, v118, v119
	v_cvt_pk_bf16_f32 v124, v124, v125
	v_cvt_pk_bf16_f32 v125, v126, v127
	global_store_dwordx2 v[2:3], v[116:117], off offset:512
	global_store_dwordx2 v[148:149], v[124:125], off offset:1536
	v_lshl_add_u64 v[2:3], v[2:3], 0, s[12:13]
	v_lshl_add_u64 v[148:149], v[148:149], 0, s[12:13]
.Lrms_done:
.LBB0_71:
	s_cmp_lg_u32 s79, 1
	s_cbranch_scc0 .LBB0_139
	s_cmp_gt_i32 s78, -1
	s_mov_b64 s[4:5], -1
	s_cbranch_scc0 .LBB0_126
	s_waitcnt vmcnt(0)
	s_barrier
	s_mov_b64 s[4:5], exec
	v_readlane_b32 s6, v254, 4
	v_readlane_b32 s7, v254, 5
	s_and_b64 s[6:7], s[4:5], s[6:7]
	s_mov_b64 exec, s[6:7]
	s_cbranch_execz .LBB0_125
	s_add_i32 s6, 0, 0x23fc0
	v_mov_b32_e32 v1, s6
	s_waitcnt vmcnt(0) expcnt(0) lgkmcnt(0)
	ds_read_b32 v3, v1
	s_add_i32 s6, 0, 0x23fc4
	v_mov_b32_e32 v1, s6
	ds_read_b32 v1, v1
	s_waitcnt lgkmcnt(1)
	v_cmp_ne_u32_e32 vcc, 0, v3
	s_cbranch_vccnz .LBB0_89
	v_readlane_b32 s6, v254, 2
	v_readlane_b32 s7, v254, 3
	s_load_dwordx2 s[10:11], s[6:7], 0x4
	s_add_u32 s6, s76, 0x10200
	s_addc_u32 s7, s77, 0
	s_add_u32 s8, s76, 0x10400
	s_addc_u32 s9, s77, 0
	s_waitcnt lgkmcnt(0)
	s_mul_i32 s49, s10, s73
	s_add_u32 s10, s76, 0x10500
	s_mul_i32 s49, s49, s11
	s_addc_u32 s11, s77, 0
	s_add_u32 s12, s76, 0x10600
	s_addc_u32 s13, s77, 0
	s_add_u32 s14, s76, 0x10700
	s_addc_u32 s15, s77, 0
	s_add_u32 s16, s76, 0x10800
	s_addc_u32 s17, s77, 0
	s_add_u32 s18, s76, 0x10900
	s_addc_u32 s19, s77, 0
	s_add_u32 s20, s76, 0x10a00
	s_addc_u32 s21, s77, 0
	s_add_u32 s22, s76, 0x10b00
	s_addc_u32 s23, s77, 0
	s_add_u32 s24, s76, 0x10c00
	s_addc_u32 s25, s77, 0
	s_add_u32 s26, s76, 0x10d00
	s_addc_u32 s27, s77, 0
	s_add_u32 s28, s76, 0x10e00
	s_addc_u32 s29, s77, 0
	s_add_u32 s30, s76, 0x10f00
	s_addc_u32 s31, s77, 0
	s_add_u32 s34, s76, 0x11000
	s_addc_u32 s35, s77, 0
	s_add_u32 s36, s76, 0x11100
	s_addc_u32 s37, s77, 0
	s_add_u32 s38, s76, 0x11200
	s_addc_u32 s39, s77, 0
	s_add_u32 s40, s76, 0x11300
	s_addc_u32 s41, s77, 0
	s_mov_b32 s50, 1
	v_mov_b32_e32 v17, 0
	s_branch .LBB0_77
